# cache policy: adaLN weight rows (read once) in the prologue also loaded non-temporal
# speedup vs baseline: 1.0267x; 1.0018x over previous
.LBB0_703:
	v_add_co_u32_e32 v12, vcc, 0xfffe8000, v46
	v_lshl_add_u64 v[32:33], v[44:45], 0, s[0:1]
	s_nop 0
	v_addc_co_u32_e32 v13, vcc, -1, v47, vcc
	global_load_dwordx4 v[56:59], v[12:13], off nt
	v_lshl_add_u64 v[12:13], v[42:43], 0, s[0:1]
	global_load_dwordx4 v[16:19], v[12:13], off offset:16
	global_load_dwordx4 v[28:31], v[12:13], off
	v_lshl_add_u64 v[14:15], v[12:13], 0, s[34:35]
	v_add_co_u32_e32 v12, vcc, s6, v12
	s_add_u32 s0, s0, 32
	s_nop 0
	v_addc_co_u32_e32 v13, vcc, 0, v13, vcc
	global_load_dwordx4 v[24:27], v[12:13], off
	s_nop 0
	global_load_dwordx4 v[12:15], v[14:15], off offset:16
	s_nop 0
	global_load_dwordx4 v[20:23], v[32:33], off offset:16
	s_nop 0
	global_load_dwordx4 v[32:35], v[32:33], off
	s_addc_u32 s1, s1, 0
	s_mov_b64 s[28:29], 0x30000
	s_cmpk_eq_i32 s0, 0x100
	s_waitcnt vmcnt(4)
	v_mul_f32_e32 v55, 0xbfb8aa3b, v28
	v_exp_f32_e32 v55, v55
	s_nop 0
	v_add_f32_e32 v55, 1.0, v55
	v_div_scale_f32 v60, s[2:3], v55, v55, v28
	v_rcp_f32_e32 v61, v60
	s_nop 0
	v_fma_f32 v62, -v60, v61, 1.0
	v_fmac_f32_e32 v61, v62, v61
	v_div_scale_f32 v62, vcc, v28, v55, v28
	v_mul_f32_e32 v63, v62, v61
	v_fma_f32 v64, -v60, v63, v62
	v_fmac_f32_e32 v63, v64, v61
	v_fma_f32 v60, -v60, v63, v62
	v_div_fmas_f32 v60, v60, v61, v63
	v_div_fixup_f32 v28, v60, v55, v28
	s_waitcnt vmcnt(3)
	v_mul_f32_e32 v55, 0xbfb8aa3b, v24
	v_exp_f32_e32 v55, v55
	v_pk_fma_f32 v[4:5], v[56:57], v[28:29], v[4:5] op_sel_hi:[1,0,1]
	v_pk_fma_f32 v[6:7], v[58:59], v[28:29], v[6:7] op_sel_hi:[1,0,1]
	v_add_f32_e32 v55, 1.0, v55
	v_div_scale_f32 v60, s[2:3], v55, v55, v24
	v_rcp_f32_e32 v61, v60
	s_nop 0
	v_fma_f32 v62, -v60, v61, 1.0
	v_fmac_f32_e32 v61, v62, v61
	v_div_scale_f32 v62, vcc, v24, v55, v24
	v_mul_f32_e32 v63, v62, v61
	v_fma_f32 v64, -v60, v63, v62
	v_fmac_f32_e32 v63, v64, v61
	v_fma_f32 v60, -v60, v63, v62
	v_div_fmas_f32 v60, v60, v61, v63
	v_div_fixup_f32 v24, v60, v55, v24
	s_waitcnt vmcnt(0)
	v_mul_f32_e32 v55, 0xbfb8aa3b, v32
	v_exp_f32_e32 v55, v55
	v_pk_fma_f32 v[8:9], v[56:57], v[24:25], v[8:9] op_sel_hi:[1,0,1]
	v_pk_fma_f32 v[10:11], v[58:59], v[24:25], v[10:11] op_sel_hi:[1,0,1]
	v_add_f32_e32 v55, 1.0, v55
	v_div_scale_f32 v60, s[2:3], v55, v55, v32
	v_rcp_f32_e32 v61, v60
	s_mov_b32 s2, 0xfffee000
	v_fma_f32 v62, -v60, v61, 1.0
	v_fmac_f32_e32 v61, v62, v61
	v_div_scale_f32 v62, vcc, v32, v55, v32
	v_mul_f32_e32 v63, v62, v61
	v_fma_f32 v64, -v60, v63, v62
	v_fmac_f32_e32 v63, v64, v61
	v_fma_f32 v60, -v60, v63, v62
	v_div_fmas_f32 v60, v60, v61, v63
	v_div_fixup_f32 v32, v60, v55, v32
	v_pk_fma_f32 v[60:61], v[56:57], v[32:33], v[0:1] op_sel_hi:[1,0,1]
	v_add_co_u32_e32 v0, vcc, s2, v46
	v_pk_fma_f32 v[62:63], v[58:59], v[32:33], v[2:3] op_sel_hi:[1,0,1]
	s_nop 0
	v_addc_co_u32_e32 v1, vcc, -1, v47, vcc
	global_load_dwordx4 v[56:59], v[0:1], off nt
	v_mul_f32_e32 v0, 0xbfb8aa3b, v29
	v_exp_f32_e32 v0, v0
	s_nop 0
	v_add_f32_e32 v0, 1.0, v0
	v_div_scale_f32 v1, s[2:3], v0, v0, v29
	v_rcp_f32_e32 v2, v1
	s_nop 0
	v_fma_f32 v3, -v1, v2, 1.0
	v_fmac_f32_e32 v2, v3, v2
	v_div_scale_f32 v3, vcc, v29, v0, v29
	v_mul_f32_e32 v24, v3, v2
	v_fma_f32 v28, -v1, v24, v3
	v_fmac_f32_e32 v24, v28, v2
	v_fma_f32 v1, -v1, v24, v3
	v_div_fmas_f32 v1, v1, v2, v24
	v_div_fixup_f32 v2, v1, v0, v29
	v_mul_f32_e32 v0, 0xbfb8aa3b, v25
	v_exp_f32_e32 v0, v0
	s_nop 0
	v_add_f32_e32 v0, 1.0, v0
	v_div_scale_f32 v1, s[2:3], v0, v0, v25
	v_rcp_f32_e32 v3, v1
	s_nop 0
	v_fma_f32 v24, -v1, v3, 1.0
	v_fmac_f32_e32 v3, v24, v3
	v_div_scale_f32 v24, vcc, v25, v0, v25
	v_mul_f32_e32 v28, v24, v3
	v_fma_f32 v29, -v1, v28, v24
	v_fmac_f32_e32 v28, v29, v3
	v_fma_f32 v1, -v1, v28, v24
	v_div_fmas_f32 v1, v1, v3, v28
	v_div_fixup_f32 v24, v1, v0, v25
	v_mul_f32_e32 v0, 0xbfb8aa3b, v33
	v_exp_f32_e32 v0, v0
	s_nop 0
	v_add_f32_e32 v0, 1.0, v0
	v_div_scale_f32 v1, s[2:3], v0, v0, v33
	v_rcp_f32_e32 v3, v1
	s_mov_b32 s2, 0xffff4000
	v_fma_f32 v25, -v1, v3, 1.0
	v_fmac_f32_e32 v3, v25, v3
	v_div_scale_f32 v25, vcc, v33, v0, v33
	v_mul_f32_e32 v28, v25, v3
	v_fma_f32 v29, -v1, v28, v25
	v_fmac_f32_e32 v28, v29, v3
	v_fma_f32 v1, -v1, v28, v25
	v_div_fmas_f32 v1, v1, v3, v28
	v_div_fixup_f32 v28, v1, v0, v33
	s_waitcnt vmcnt(0)
	v_pk_fma_f32 v[0:1], v[58:59], v[2:3], v[6:7] op_sel_hi:[1,0,1]
	v_pk_fma_f32 v[6:7], v[56:57], v[2:3], v[4:5] op_sel_hi:[1,0,1]
	v_pk_fma_f32 v[2:3], v[58:59], v[24:25], v[10:11] op_sel_hi:[1,0,1]
	v_pk_fma_f32 v[8:9], v[56:57], v[24:25], v[8:9] op_sel_hi:[1,0,1]
	v_add_co_u32_e32 v24, vcc, s2, v46
	v_pk_fma_f32 v[4:5], v[58:59], v[28:29], v[62:63] op_sel_hi:[1,0,1]
	s_nop 0
	v_addc_co_u32_e32 v25, vcc, -1, v47, vcc
	v_pk_fma_f32 v[10:11], v[56:57], v[28:29], v[60:61] op_sel_hi:[1,0,1]
	global_load_dwordx4 v[56:59], v[24:25], off nt
	v_mul_f32_e32 v24, 0xbfb8aa3b, v30
	v_exp_f32_e32 v24, v24
	s_nop 0
	v_add_f32_e32 v24, 1.0, v24
	v_div_scale_f32 v25, s[2:3], v24, v24, v30
	v_rcp_f32_e32 v28, v25
	s_nop 0
	v_fma_f32 v29, -v25, v28, 1.0
	v_fmac_f32_e32 v28, v29, v28
	v_div_scale_f32 v29, vcc, v30, v24, v30
	v_mul_f32_e32 v32, v29, v28
	v_fma_f32 v33, -v25, v32, v29
	v_fmac_f32_e32 v32, v33, v28
	v_fma_f32 v25, -v25, v32, v29
	v_div_fmas_f32 v25, v25, v28, v32
	v_div_fixup_f32 v24, v25, v24, v30
	v_mul_f32_e32 v25, 0xbfb8aa3b, v26
	v_exp_f32_e32 v25, v25
	s_nop 0
	v_add_f32_e32 v25, 1.0, v25
	v_div_scale_f32 v28, s[2:3], v25, v25, v26
	v_rcp_f32_e32 v29, v28
	s_nop 0
	v_fma_f32 v30, -v28, v29, 1.0
	v_fmac_f32_e32 v29, v30, v29
	v_div_scale_f32 v30, vcc, v26, v25, v26
	v_mul_f32_e32 v32, v30, v29
	v_fma_f32 v33, -v28, v32, v30
	v_fmac_f32_e32 v32, v33, v29
	v_fma_f32 v28, -v28, v32, v30
	v_div_fmas_f32 v28, v28, v29, v32
	v_div_fixup_f32 v26, v28, v25, v26
	v_mul_f32_e32 v25, 0xbfb8aa3b, v34
	v_exp_f32_e32 v25, v25
	s_waitcnt vmcnt(0)
	v_pk_fma_f32 v[8:9], v[56:57], v[26:27], v[8:9] op_sel_hi:[1,0,1]
	v_add_f32_e32 v25, 1.0, v25
	v_div_scale_f32 v28, s[2:3], v25, v25, v34
	v_rcp_f32_e32 v29, v28
	s_movk_i32 s2, 0xa000
	v_pk_fma_f32 v[6:7], v[56:57], v[24:25], v[6:7] op_sel_hi:[1,0,1]
	v_pk_fma_f32 v[0:1], v[58:59], v[24:25], v[0:1] op_sel_hi:[1,0,1]
	v_fma_f32 v30, -v28, v29, 1.0
	v_fmac_f32_e32 v29, v30, v29
	v_div_scale_f32 v30, vcc, v34, v25, v34
	v_mul_f32_e32 v32, v30, v29
	v_fma_f32 v33, -v28, v32, v30
	v_fmac_f32_e32 v32, v33, v29
	v_fma_f32 v28, -v28, v32, v30
	v_div_fmas_f32 v28, v28, v29, v32
	v_add_co_u32_e32 v24, vcc, s2, v46
	v_div_fixup_f32 v28, v28, v25, v34
	s_nop 0
	v_addc_co_u32_e32 v25, vcc, -1, v47, vcc
	v_pk_fma_f32 v[2:3], v[58:59], v[26:27], v[2:3] op_sel_hi:[1,0,1]
	v_pk_fma_f32 v[10:11], v[56:57], v[28:29], v[10:11] op_sel_hi:[1,0,1]
	v_pk_fma_f32 v[4:5], v[58:59], v[28:29], v[4:5] op_sel_hi:[1,0,1]
	global_load_dwordx4 v[56:59], v[24:25], off nt
	v_mul_f32_e32 v24, 0xbfb8aa3b, v31
	v_exp_f32_e32 v24, v24
	s_nop 0
	v_add_f32_e32 v24, 1.0, v24
	v_div_scale_f32 v25, s[2:3], v24, v24, v31
	v_rcp_f32_e32 v26, v25
	s_nop 0
	v_fma_f32 v28, -v25, v26, 1.0
	v_fmac_f32_e32 v26, v28, v26
	v_div_scale_f32 v28, vcc, v31, v24, v31
	v_mul_f32_e32 v29, v28, v26
	v_fma_f32 v30, -v25, v29, v28
	v_fmac_f32_e32 v29, v30, v26
	v_fma_f32 v25, -v25, v29, v28
	v_div_fmas_f32 v25, v25, v26, v29
	v_div_fixup_f32 v24, v25, v24, v31
	v_mul_f32_e32 v25, 0xbfb8aa3b, v27
	v_exp_f32_e32 v25, v25
	s_nop 0
	v_add_f32_e32 v25, 1.0, v25
	v_div_scale_f32 v26, s[2:3], v25, v25, v27
	v_rcp_f32_e32 v28, v26
	s_nop 0
	v_fma_f32 v29, -v26, v28, 1.0
	v_fmac_f32_e32 v28, v29, v28
	v_div_scale_f32 v29, vcc, v27, v25, v27
	v_mul_f32_e32 v30, v29, v28
	v_fma_f32 v31, -v26, v30, v29
	v_fmac_f32_e32 v30, v31, v28
	v_fma_f32 v26, -v26, v30, v29
	v_div_fmas_f32 v26, v26, v28, v30
	v_div_fixup_f32 v26, v26, v25, v27
	v_mul_f32_e32 v25, 0xbfb8aa3b, v35
	v_exp_f32_e32 v25, v25
	s_nop 0
	v_add_f32_e32 v25, 1.0, v25
	v_div_scale_f32 v27, s[2:3], v25, v25, v35
	v_rcp_f32_e32 v28, v27
	s_waitcnt vmcnt(0)
	v_pk_fma_f32 v[0:1], v[58:59], v[24:25], v[0:1] op_sel_hi:[1,0,1]
	v_fma_f32 v29, -v27, v28, 1.0
	v_fmac_f32_e32 v28, v29, v28
	v_div_scale_f32 v29, vcc, v35, v25, v35
	v_mul_f32_e32 v30, v29, v28
	v_fma_f32 v31, -v27, v30, v29
	v_fmac_f32_e32 v30, v31, v28
	v_fma_f32 v27, -v27, v30, v29
	v_div_fmas_f32 v27, v27, v28, v30
	v_div_fixup_f32 v28, v27, v25, v35
	v_pk_fma_f32 v[6:7], v[56:57], v[24:25], v[6:7] op_sel_hi:[1,0,1]
	v_pk_fma_f32 v[2:3], v[58:59], v[26:27], v[2:3] op_sel_hi:[1,0,1]
	v_pk_fma_f32 v[8:9], v[56:57], v[26:27], v[8:9] op_sel_hi:[1,0,1]
	global_load_dwordx4 v[24:27], v[46:47], off nt
	v_pk_fma_f32 v[4:5], v[58:59], v[28:29], v[4:5] op_sel_hi:[1,0,1]
	v_pk_fma_f32 v[10:11], v[56:57], v[28:29], v[10:11] op_sel_hi:[1,0,1]
	v_mul_f32_e32 v28, 0xbfb8aa3b, v16
	v_exp_f32_e32 v28, v28
	s_nop 0
	v_add_f32_e32 v28, 1.0, v28
	v_div_scale_f32 v29, s[2:3], v28, v28, v16
	v_rcp_f32_e32 v30, v29
	s_nop 0
	v_fma_f32 v31, -v29, v30, 1.0
	v_fmac_f32_e32 v30, v31, v30
	v_div_scale_f32 v31, vcc, v16, v28, v16
	v_mul_f32_e32 v32, v31, v30
	v_fma_f32 v33, -v29, v32, v31
	v_fmac_f32_e32 v32, v33, v30
	v_fma_f32 v29, -v29, v32, v31
	v_div_fmas_f32 v29, v29, v30, v32
	v_div_fixup_f32 v16, v29, v28, v16
	v_mul_f32_e32 v28, 0xbfb8aa3b, v12
	v_exp_f32_e32 v28, v28
	s_waitcnt vmcnt(0)
	v_pk_fma_f32 v[6:7], v[24:25], v[16:17], v[6:7] op_sel_hi:[1,0,1]
	v_add_f32_e32 v28, 1.0, v28
	v_div_scale_f32 v29, s[2:3], v28, v28, v12
	v_rcp_f32_e32 v30, v29
	v_pk_fma_f32 v[0:1], v[26:27], v[16:17], v[0:1] op_sel_hi:[1,0,1]
	v_fma_f32 v31, -v29, v30, 1.0
	v_fmac_f32_e32 v30, v31, v30
	v_div_scale_f32 v31, vcc, v12, v28, v12
	v_mul_f32_e32 v32, v31, v30
	v_fma_f32 v33, -v29, v32, v31
	v_fmac_f32_e32 v32, v33, v30
	v_fma_f32 v29, -v29, v32, v31
	v_div_fmas_f32 v29, v29, v30, v32
	v_div_fixup_f32 v12, v29, v28, v12
	v_mul_f32_e32 v28, 0xbfb8aa3b, v20
	v_exp_f32_e32 v28, v28
	v_pk_fma_f32 v[8:9], v[24:25], v[12:13], v[8:9] op_sel_hi:[1,0,1]
	v_pk_fma_f32 v[2:3], v[26:27], v[12:13], v[2:3] op_sel_hi:[1,0,1]
	v_mul_f32_e32 v12, 0xbfb8aa3b, v17
	v_add_f32_e32 v28, 1.0, v28
	v_div_scale_f32 v29, s[2:3], v28, v28, v20
	v_rcp_f32_e32 v30, v29
	v_exp_f32_e32 v12, v12
	v_fma_f32 v31, -v29, v30, 1.0
	v_fmac_f32_e32 v30, v31, v30
	v_div_scale_f32 v31, vcc, v20, v28, v20
	v_mul_f32_e32 v32, v31, v30
	v_fma_f32 v33, -v29, v32, v31
	v_fmac_f32_e32 v32, v33, v30
	v_fma_f32 v29, -v29, v32, v31
	v_div_fmas_f32 v29, v29, v30, v32
	v_div_fixup_f32 v20, v29, v28, v20
	v_pk_fma_f32 v[10:11], v[24:25], v[20:21], v[10:11] op_sel_hi:[1,0,1]
	v_add_co_u32_e32 v24, vcc, s67, v46
	v_pk_fma_f32 v[4:5], v[26:27], v[20:21], v[4:5] op_sel_hi:[1,0,1]
	s_nop 0
	v_addc_co_u32_e32 v25, vcc, 0, v47, vcc
	global_load_dwordx4 v[24:27], v[24:25], off nt
	v_add_f32_e32 v12, 1.0, v12
	v_div_scale_f32 v16, s[2:3], v12, v12, v17
	v_rcp_f32_e32 v20, v16
	s_nop 0
	v_fma_f32 v28, -v16, v20, 1.0
	v_fmac_f32_e32 v20, v28, v20
	v_div_scale_f32 v28, vcc, v17, v12, v17
	v_mul_f32_e32 v29, v28, v20
	v_fma_f32 v30, -v16, v29, v28
	v_fmac_f32_e32 v29, v30, v20
	v_fma_f32 v16, -v16, v29, v28
	v_div_fmas_f32 v16, v16, v20, v29
	v_div_fixup_f32 v12, v16, v12, v17
	v_mul_f32_e32 v16, 0xbfb8aa3b, v13
	v_exp_f32_e32 v16, v16
	s_nop 0
	v_add_f32_e32 v16, 1.0, v16
	v_div_scale_f32 v17, s[2:3], v16, v16, v13
	v_rcp_f32_e32 v20, v17
	s_nop 0
	v_fma_f32 v28, -v17, v20, 1.0
	v_fmac_f32_e32 v20, v28, v20
	v_div_scale_f32 v28, vcc, v13, v16, v13
	v_mul_f32_e32 v29, v28, v20
	v_fma_f32 v30, -v17, v29, v28
	v_fmac_f32_e32 v29, v30, v20
	v_fma_f32 v17, -v17, v29, v28
	v_div_fmas_f32 v17, v17, v20, v29
	v_div_fixup_f32 v16, v17, v16, v13
	v_mul_f32_e32 v13, 0xbfb8aa3b, v21
	v_exp_f32_e32 v13, v13
	s_nop 0
	v_add_f32_e32 v13, 1.0, v13
	v_div_scale_f32 v17, s[2:3], v13, v13, v21
	v_rcp_f32_e32 v20, v17
	s_waitcnt vmcnt(0)
	v_pk_fma_f32 v[0:1], v[26:27], v[12:13], v[0:1] op_sel_hi:[1,0,1]
	v_fma_f32 v28, -v17, v20, 1.0
	v_fmac_f32_e32 v20, v28, v20
	v_div_scale_f32 v28, vcc, v21, v13, v21
	v_mul_f32_e32 v29, v28, v20
	v_fma_f32 v30, -v17, v29, v28
	v_fmac_f32_e32 v29, v30, v20
	v_fma_f32 v17, -v17, v29, v28
	v_div_fmas_f32 v17, v17, v20, v29
	v_pk_fma_f32 v[6:7], v[24:25], v[12:13], v[6:7] op_sel_hi:[1,0,1]
	v_add_co_u32_e32 v12, vcc, s64, v46
	v_div_fixup_f32 v20, v17, v13, v21
	s_nop 0
	v_addc_co_u32_e32 v13, vcc, 0, v47, vcc
	v_pk_fma_f32 v[2:3], v[26:27], v[16:17], v[2:3] op_sel_hi:[1,0,1]
	v_pk_fma_f32 v[8:9], v[24:25], v[16:17], v[8:9] op_sel_hi:[1,0,1]
	v_pk_fma_f32 v[4:5], v[26:27], v[20:21], v[4:5] op_sel_hi:[1,0,1]
	v_pk_fma_f32 v[10:11], v[24:25], v[20:21], v[10:11] op_sel_hi:[1,0,1]
	global_load_dwordx4 v[24:27], v[12:13], off nt
	v_mul_f32_e32 v12, 0xbfb8aa3b, v18
	v_exp_f32_e32 v12, v12
	s_nop 0
	v_add_f32_e32 v12, 1.0, v12
	v_div_scale_f32 v13, s[2:3], v12, v12, v18
	v_rcp_f32_e32 v16, v13
	s_nop 0
	v_fma_f32 v17, -v13, v16, 1.0
	v_fmac_f32_e32 v16, v17, v16
	v_div_scale_f32 v17, vcc, v18, v12, v18
	v_mul_f32_e32 v20, v17, v16
	v_fma_f32 v21, -v13, v20, v17
	v_fmac_f32_e32 v20, v21, v16
	v_fma_f32 v13, -v13, v20, v17
	v_div_fmas_f32 v13, v13, v16, v20
	v_div_fixup_f32 v12, v13, v12, v18
	v_mul_f32_e32 v13, 0xbfb8aa3b, v14
	v_exp_f32_e32 v13, v13
	s_nop 0
	v_add_f32_e32 v13, 1.0, v13
	v_div_scale_f32 v16, s[2:3], v13, v13, v14
	v_rcp_f32_e32 v17, v16
	s_nop 0
	v_fma_f32 v18, -v16, v17, 1.0
	v_fmac_f32_e32 v17, v18, v17
	v_div_scale_f32 v18, vcc, v14, v13, v14
	v_mul_f32_e32 v20, v18, v17
	v_fma_f32 v21, -v16, v20, v18
	v_fmac_f32_e32 v20, v21, v17
	v_fma_f32 v16, -v16, v20, v18
	v_div_fmas_f32 v16, v16, v17, v20
	v_div_fixup_f32 v14, v16, v13, v14
	v_mul_f32_e32 v13, 0xbfb8aa3b, v22
	v_exp_f32_e32 v13, v13
	s_waitcnt vmcnt(0)
	v_pk_fma_f32 v[8:9], v[24:25], v[14:15], v[8:9] op_sel_hi:[1,0,1]
	v_add_f32_e32 v13, 1.0, v13
	v_div_scale_f32 v16, s[2:3], v13, v13, v22
	v_rcp_f32_e32 v17, v16
	s_mov_b32 s2, 0x12000
	v_fma_f32 v18, -v16, v17, 1.0
	v_fmac_f32_e32 v17, v18, v17
	v_div_scale_f32 v18, vcc, v22, v13, v22
	v_mul_f32_e32 v20, v18, v17
	v_fma_f32 v21, -v16, v20, v18
	v_fmac_f32_e32 v20, v21, v17
	v_fma_f32 v16, -v16, v20, v18
	v_div_fmas_f32 v16, v16, v17, v20
	v_pk_fma_f32 v[20:21], v[24:25], v[12:13], v[6:7] op_sel_hi:[1,0,1]
	v_pk_fma_f32 v[6:7], v[26:27], v[12:13], v[0:1] op_sel_hi:[1,0,1]
	v_add_co_u32_e32 v0, vcc, s2, v46
	v_div_fixup_f32 v16, v16, v13, v22
	s_nop 0
	v_addc_co_u32_e32 v1, vcc, 0, v47, vcc
	v_pk_fma_f32 v[12:13], v[26:27], v[14:15], v[2:3] op_sel_hi:[1,0,1]
	global_load_dwordx4 v[0:3], v[0:1], off nt
	v_pk_fma_f32 v[24:25], v[24:25], v[16:17], v[10:11] op_sel_hi:[1,0,1]
	v_pk_fma_f32 v[16:17], v[26:27], v[16:17], v[4:5] op_sel_hi:[1,0,1]
	v_mul_f32_e32 v4, 0xbfb8aa3b, v19
	v_exp_f32_e32 v4, v4
	v_lshl_add_u64 v[46:47], v[46:47], 0, s[28:29]
	v_add_f32_e32 v4, 1.0, v4
	v_div_scale_f32 v5, s[2:3], v4, v4, v19
	v_rcp_f32_e32 v10, v5
	s_nop 0
	v_fma_f32 v11, -v5, v10, 1.0
	v_fmac_f32_e32 v10, v11, v10
	v_div_scale_f32 v11, vcc, v19, v4, v19
	v_mul_f32_e32 v14, v11, v10
	v_fma_f32 v18, -v5, v14, v11
	v_fmac_f32_e32 v14, v18, v10
	v_fma_f32 v5, -v5, v14, v11
	v_div_fmas_f32 v5, v5, v10, v14
	v_div_fixup_f32 v4, v5, v4, v19
	v_mul_f32_e32 v5, 0xbfb8aa3b, v15
	v_exp_f32_e32 v5, v5
	s_nop 0
	v_add_f32_e32 v5, 1.0, v5
	v_div_scale_f32 v10, s[2:3], v5, v5, v15
	v_rcp_f32_e32 v11, v10
	s_nop 0
	v_fma_f32 v14, -v10, v11, 1.0
	v_fmac_f32_e32 v11, v14, v11
	v_div_scale_f32 v14, vcc, v15, v5, v15
	v_mul_f32_e32 v18, v14, v11
	v_fma_f32 v19, -v10, v18, v14
	v_fmac_f32_e32 v18, v19, v11
	v_fma_f32 v10, -v10, v18, v14
	v_div_fmas_f32 v10, v10, v11, v18
	v_div_fixup_f32 v14, v10, v5, v15
	v_mul_f32_e32 v5, 0xbfb8aa3b, v23
	v_exp_f32_e32 v5, v5
	s_nop 0
	v_add_f32_e32 v5, 1.0, v5
	v_div_scale_f32 v10, s[2:3], v5, v5, v23
	v_rcp_f32_e32 v11, v10
	s_waitcnt vmcnt(0)
	v_pk_fma_f32 v[6:7], v[2:3], v[4:5], v[6:7] op_sel_hi:[1,0,1]
	v_fma_f32 v15, -v10, v11, 1.0
	v_fmac_f32_e32 v11, v15, v11
	v_div_scale_f32 v15, vcc, v23, v5, v23
	v_mul_f32_e32 v18, v15, v11
	v_fma_f32 v19, -v10, v18, v15
	v_fmac_f32_e32 v18, v19, v11
	v_fma_f32 v10, -v10, v18, v15
	v_div_fmas_f32 v10, v10, v11, v18
	v_div_fixup_f32 v18, v10, v5, v23
	v_pk_fma_f32 v[4:5], v[0:1], v[4:5], v[20:21] op_sel_hi:[1,0,1]
	v_pk_fma_f32 v[10:11], v[2:3], v[14:15], v[12:13] op_sel_hi:[1,0,1]
	v_pk_fma_f32 v[8:9], v[0:1], v[14:15], v[8:9] op_sel_hi:[1,0,1]
	v_pk_fma_f32 v[2:3], v[2:3], v[18:19], v[16:17] op_sel_hi:[1,0,1]
	v_pk_fma_f32 v[0:1], v[0:1], v[18:19], v[24:25] op_sel_hi:[1,0,1]
	s_cbranch_scc0 .LBB0_703
	v_and_b32_e32 v12, 15, v37
	v_readlane_b32 s8, v254, 9
	v_lshl_or_b32 v12, v54, 4, v12
	v_readlane_b32 s10, v254, 11
	v_readlane_b32 s11, v254, 12
	v_lshl_add_u32 v14, v12, 1, v12
	v_readlane_b32 s9, v254, 10
	v_mov_b64_e32 v[12:13], s[10:11]
	v_mad_i64_i32 v[12:13], s[0:1], v14, s67, v[12:13]
	v_lshl_add_u64 v[12:13], v[40:41], 2, v[12:13]
	global_store_dwordx4 v[12:13], v[4:7], off
	v_readlane_b32 s12, v254, 13
	v_readlane_b32 s13, v254, 14
	v_add_co_u32_e32 v4, vcc, 0x6000, v12
	v_readlane_b32 s14, v254, 15
	s_nop 0
	v_addc_co_u32_e32 v5, vcc, 0, v13, vcc
	global_store_dwordx4 v[4:5], v[8:11], off
	v_add_co_u32_e32 v4, vcc, 0xc000, v12
	v_readlane_b32 s15, v254, 16
	s_nop 0
	v_addc_co_u32_e32 v5, vcc, 0, v13, vcc
	v_readlane_b32 s16, v254, 17
	v_readlane_b32 s17, v254, 18
	v_readlane_b32 s18, v254, 19
	v_readlane_b32 s19, v254, 20
	v_readlane_b32 s20, v254, 21
	v_readlane_b32 s21, v254, 22
	v_readlane_b32 s22, v254, 23
	v_readlane_b32 s23, v254, 24
	global_store_dwordx4 v[4:5], v[0:3], off
	s_branch .LBB0_582
